# adds batched cross-lane reductions in the phase-1 shift GEMVs (6 waits per weight row instead of 102)
# speedup vs baseline: 1.0114x; 1.0114x over previous
.LBB0_113:
	v_lshlrev_b32_e32 v26, 16, v12
	v_and_b32_e32 v12, 0xffff0000, v12
	v_lshlrev_b32_e32 v27, 16, v13
	v_and_b32_e32 v13, 0xffff0000, v13
	v_lshlrev_b32_e32 v28, 16, v14
	v_and_b32_e32 v14, 0xffff0000, v14
	v_lshlrev_b32_e32 v29, 16, v15
	v_and_b32_e32 v15, 0xffff0000, v15
	v_lshlrev_b32_e32 v30, 16, v8
	v_and_b32_e32 v8, 0xffff0000, v8
	v_lshlrev_b32_e32 v31, 16, v9
	v_and_b32_e32 v9, 0xffff0000, v9
	v_lshlrev_b32_e32 v32, 16, v10
	v_and_b32_e32 v10, 0xffff0000, v10
	v_lshlrev_b32_e32 v33, 16, v11
	v_and_b32_e32 v11, 0xffff0000, v11
	v_add_u32_e32 v101, 0x8000, v20
	v_add_u32_e32 v102, 0x10000, v20
	s_mov_b64 s[10:11], s[6:7]
	s_waitcnt lgkmcnt(0)
	ds_read_b128 v[34:37], v20 offset:2048
	ds_read_b128 v[38:41], v20
	ds_read_b128 v[42:45], v20 offset:16
	ds_read_b128 v[46:49], v20 offset:2064
	ds_read_b128 v[104:107], v20 offset:6144
	ds_read_b128 v[108:111], v20 offset:4096
	ds_read_b128 v[112:115], v20 offset:4112
	ds_read_b128 v[116:119], v20 offset:6160
	s_waitcnt lgkmcnt(4)
	v_mul_f32_e32 v52, v34, v30
	v_mul_f32_e32 v100, v35, v8
	v_fmac_f32_e32 v52, v38, v26
	v_add_f32_e32 v52, 0, v52
	v_fmac_f32_e32 v100, v39, v12
	v_add_f32_e32 v52, v52, v100
	v_mul_f32_e32 v100, v36, v31
	v_fmac_f32_e32 v100, v40, v27
	v_add_f32_e32 v52, v52, v100
	v_mul_f32_e32 v100, v37, v9
	v_fmac_f32_e32 v100, v41, v13
	v_add_f32_e32 v52, v52, v100
	v_mul_f32_e32 v100, v46, v32
	v_fmac_f32_e32 v100, v42, v28
	v_add_f32_e32 v52, v52, v100
	v_mul_f32_e32 v100, v47, v10
	v_fmac_f32_e32 v100, v43, v14
	v_add_f32_e32 v52, v52, v100
	v_mul_f32_e32 v100, v48, v33
	v_fmac_f32_e32 v100, v44, v29
	v_add_f32_e32 v52, v52, v100
	v_mul_f32_e32 v100, v49, v11
	v_fmac_f32_e32 v100, v45, v15
	v_add_f32_e32 v52, v52, v100
	ds_read_b128 v[34:37], v20 offset:10240
	ds_read_b128 v[38:41], v20 offset:8192
	ds_read_b128 v[42:45], v20 offset:8208
	ds_read_b128 v[46:49], v20 offset:10256
	s_waitcnt lgkmcnt(4)
	v_mul_f32_e32 v53, v104, v30
	v_mul_f32_e32 v100, v105, v8
	v_fmac_f32_e32 v53, v108, v26
	v_add_f32_e32 v53, 0, v53
	v_fmac_f32_e32 v100, v109, v12
	v_add_f32_e32 v53, v53, v100
	v_mul_f32_e32 v100, v106, v31
	v_fmac_f32_e32 v100, v110, v27
	v_add_f32_e32 v53, v53, v100
	v_mul_f32_e32 v100, v107, v9
	v_fmac_f32_e32 v100, v111, v13
	v_add_f32_e32 v53, v53, v100
	v_mul_f32_e32 v100, v116, v32
	v_fmac_f32_e32 v100, v112, v28
	v_add_f32_e32 v53, v53, v100
	v_mul_f32_e32 v100, v117, v10
	v_fmac_f32_e32 v100, v113, v14
	v_add_f32_e32 v53, v53, v100
	v_mul_f32_e32 v100, v118, v33
	v_fmac_f32_e32 v100, v114, v29
	v_add_f32_e32 v53, v53, v100
	v_mul_f32_e32 v100, v119, v11
	v_fmac_f32_e32 v100, v115, v15
	v_add_f32_e32 v53, v53, v100
	ds_read_b128 v[104:107], v20 offset:14336
	ds_read_b128 v[108:111], v20 offset:12288
	ds_read_b128 v[112:115], v20 offset:12304
	ds_read_b128 v[116:119], v20 offset:14352
	s_waitcnt lgkmcnt(4)
	v_mul_f32_e32 v54, v34, v30
	v_mul_f32_e32 v100, v35, v8
	v_fmac_f32_e32 v54, v38, v26
	v_add_f32_e32 v54, 0, v54
	v_fmac_f32_e32 v100, v39, v12
	v_add_f32_e32 v54, v54, v100
	v_mul_f32_e32 v100, v36, v31
	v_fmac_f32_e32 v100, v40, v27
	v_add_f32_e32 v54, v54, v100
	v_mul_f32_e32 v100, v37, v9
	v_fmac_f32_e32 v100, v41, v13
	v_add_f32_e32 v54, v54, v100
	v_mul_f32_e32 v100, v46, v32
	v_fmac_f32_e32 v100, v42, v28
	v_add_f32_e32 v54, v54, v100
	v_mul_f32_e32 v100, v47, v10
	v_fmac_f32_e32 v100, v43, v14
	v_add_f32_e32 v54, v54, v100
	v_mul_f32_e32 v100, v48, v33
	v_fmac_f32_e32 v100, v44, v29
	v_add_f32_e32 v54, v54, v100
	v_mul_f32_e32 v100, v49, v11
	v_fmac_f32_e32 v100, v45, v15
	v_add_f32_e32 v54, v54, v100
	ds_read_b128 v[34:37], v20 offset:18432
	ds_read_b128 v[38:41], v20 offset:16384
	ds_read_b128 v[42:45], v20 offset:16400
	ds_read_b128 v[46:49], v20 offset:18448
	s_waitcnt lgkmcnt(4)
	v_mul_f32_e32 v55, v104, v30
	v_mul_f32_e32 v100, v105, v8
	v_fmac_f32_e32 v55, v108, v26
	v_add_f32_e32 v55, 0, v55
	v_fmac_f32_e32 v100, v109, v12
	v_add_f32_e32 v55, v55, v100
	v_mul_f32_e32 v100, v106, v31
	v_fmac_f32_e32 v100, v110, v27
	v_add_f32_e32 v55, v55, v100
	v_mul_f32_e32 v100, v107, v9
	v_fmac_f32_e32 v100, v111, v13
	v_add_f32_e32 v55, v55, v100
	v_mul_f32_e32 v100, v116, v32
	v_fmac_f32_e32 v100, v112, v28
	v_add_f32_e32 v55, v55, v100
	v_mul_f32_e32 v100, v117, v10
	v_fmac_f32_e32 v100, v113, v14
	v_add_f32_e32 v55, v55, v100
	v_mul_f32_e32 v100, v118, v33
	v_fmac_f32_e32 v100, v114, v29
	v_add_f32_e32 v55, v55, v100
	v_mul_f32_e32 v100, v119, v11
	v_fmac_f32_e32 v100, v115, v15
	v_add_f32_e32 v55, v55, v100
	ds_read_b128 v[104:107], v20 offset:22528
	ds_read_b128 v[108:111], v20 offset:20480
	ds_read_b128 v[112:115], v20 offset:20496
	ds_read_b128 v[116:119], v20 offset:22544
	s_waitcnt lgkmcnt(4)
	v_mul_f32_e32 v56, v34, v30
	v_mul_f32_e32 v100, v35, v8
	v_fmac_f32_e32 v56, v38, v26
	v_add_f32_e32 v56, 0, v56
	v_fmac_f32_e32 v100, v39, v12
	v_add_f32_e32 v56, v56, v100
	v_mul_f32_e32 v100, v36, v31
	v_fmac_f32_e32 v100, v40, v27
	v_add_f32_e32 v56, v56, v100
	v_mul_f32_e32 v100, v37, v9
	v_fmac_f32_e32 v100, v41, v13
	v_add_f32_e32 v56, v56, v100
	v_mul_f32_e32 v100, v46, v32
	v_fmac_f32_e32 v100, v42, v28
	v_add_f32_e32 v56, v56, v100
	v_mul_f32_e32 v100, v47, v10
	v_fmac_f32_e32 v100, v43, v14
	v_add_f32_e32 v56, v56, v100
	v_mul_f32_e32 v100, v48, v33
	v_fmac_f32_e32 v100, v44, v29
	v_add_f32_e32 v56, v56, v100
	v_mul_f32_e32 v100, v49, v11
	v_fmac_f32_e32 v100, v45, v15
	v_add_f32_e32 v56, v56, v100
	ds_read_b128 v[34:37], v20 offset:26624
	ds_read_b128 v[38:41], v20 offset:24576
	ds_read_b128 v[42:45], v20 offset:24592
	ds_read_b128 v[46:49], v20 offset:26640
	s_waitcnt lgkmcnt(4)
	v_mul_f32_e32 v57, v104, v30
	v_mul_f32_e32 v100, v105, v8
	v_fmac_f32_e32 v57, v108, v26
	v_add_f32_e32 v57, 0, v57
	v_fmac_f32_e32 v100, v109, v12
	v_add_f32_e32 v57, v57, v100
	v_mul_f32_e32 v100, v106, v31
	v_fmac_f32_e32 v100, v110, v27
	v_add_f32_e32 v57, v57, v100
	v_mul_f32_e32 v100, v107, v9
	v_fmac_f32_e32 v100, v111, v13
	v_add_f32_e32 v57, v57, v100
	v_mul_f32_e32 v100, v116, v32
	v_fmac_f32_e32 v100, v112, v28
	v_add_f32_e32 v57, v57, v100
	v_mul_f32_e32 v100, v117, v10
	v_fmac_f32_e32 v100, v113, v14
	v_add_f32_e32 v57, v57, v100
	v_mul_f32_e32 v100, v118, v33
	v_fmac_f32_e32 v100, v114, v29
	v_add_f32_e32 v57, v57, v100
	v_mul_f32_e32 v100, v119, v11
	v_fmac_f32_e32 v100, v115, v15
	v_add_f32_e32 v57, v57, v100
	ds_read_b128 v[104:107], v20 offset:30720
	ds_read_b128 v[108:111], v20 offset:28672
	ds_read_b128 v[112:115], v20 offset:28688
	ds_read_b128 v[116:119], v20 offset:30736
	s_waitcnt lgkmcnt(4)
	v_mul_f32_e32 v58, v34, v30
	v_mul_f32_e32 v100, v35, v8
	v_fmac_f32_e32 v58, v38, v26
	v_add_f32_e32 v58, 0, v58
	v_fmac_f32_e32 v100, v39, v12
	v_add_f32_e32 v58, v58, v100
	v_mul_f32_e32 v100, v36, v31
	v_fmac_f32_e32 v100, v40, v27
	v_add_f32_e32 v58, v58, v100
	v_mul_f32_e32 v100, v37, v9
	v_fmac_f32_e32 v100, v41, v13
	v_add_f32_e32 v58, v58, v100
	v_mul_f32_e32 v100, v46, v32
	v_fmac_f32_e32 v100, v42, v28
	v_add_f32_e32 v58, v58, v100
	v_mul_f32_e32 v100, v47, v10
	v_fmac_f32_e32 v100, v43, v14
	v_add_f32_e32 v58, v58, v100
	v_mul_f32_e32 v100, v48, v33
	v_fmac_f32_e32 v100, v44, v29
	v_add_f32_e32 v58, v58, v100
	v_mul_f32_e32 v100, v49, v11
	v_fmac_f32_e32 v100, v45, v15
	v_add_f32_e32 v58, v58, v100
	ds_read_b128 v[34:37], v101 offset:2048
	ds_read_b128 v[38:41], v101
	ds_read_b128 v[42:45], v101 offset:16
	ds_read_b128 v[46:49], v101 offset:2064
	s_waitcnt lgkmcnt(4)
	v_mul_f32_e32 v59, v104, v30
	v_mul_f32_e32 v100, v105, v8
	v_fmac_f32_e32 v59, v108, v26
	v_add_f32_e32 v59, 0, v59
	v_fmac_f32_e32 v100, v109, v12
	v_add_f32_e32 v59, v59, v100
	v_mul_f32_e32 v100, v106, v31
	v_fmac_f32_e32 v100, v110, v27
	v_add_f32_e32 v59, v59, v100
	v_mul_f32_e32 v100, v107, v9
	v_fmac_f32_e32 v100, v111, v13
	v_add_f32_e32 v59, v59, v100
	v_mul_f32_e32 v100, v116, v32
	v_fmac_f32_e32 v100, v112, v28
	v_add_f32_e32 v59, v59, v100
	v_mul_f32_e32 v100, v117, v10
	v_fmac_f32_e32 v100, v113, v14
	v_add_f32_e32 v59, v59, v100
	v_mul_f32_e32 v100, v118, v33
	v_fmac_f32_e32 v100, v114, v29
	v_add_f32_e32 v59, v59, v100
	v_mul_f32_e32 v100, v119, v11
	v_fmac_f32_e32 v100, v115, v15
	v_add_f32_e32 v59, v59, v100
	ds_read_b128 v[104:107], v101 offset:6144
	ds_read_b128 v[108:111], v101 offset:4096
	ds_read_b128 v[112:115], v101 offset:4112
	ds_read_b128 v[116:119], v101 offset:6160
	s_waitcnt lgkmcnt(4)
	v_mul_f32_e32 v60, v34, v30
	v_mul_f32_e32 v100, v35, v8
	v_fmac_f32_e32 v60, v38, v26
	v_add_f32_e32 v60, 0, v60
	v_fmac_f32_e32 v100, v39, v12
	v_add_f32_e32 v60, v60, v100
	v_mul_f32_e32 v100, v36, v31
	v_fmac_f32_e32 v100, v40, v27
	v_add_f32_e32 v60, v60, v100
	v_mul_f32_e32 v100, v37, v9
	v_fmac_f32_e32 v100, v41, v13
	v_add_f32_e32 v60, v60, v100
	v_mul_f32_e32 v100, v46, v32
	v_fmac_f32_e32 v100, v42, v28
	v_add_f32_e32 v60, v60, v100
	v_mul_f32_e32 v100, v47, v10
	v_fmac_f32_e32 v100, v43, v14
	v_add_f32_e32 v60, v60, v100
	v_mul_f32_e32 v100, v48, v33
	v_fmac_f32_e32 v100, v44, v29
	v_add_f32_e32 v60, v60, v100
	v_mul_f32_e32 v100, v49, v11
	v_fmac_f32_e32 v100, v45, v15
	v_add_f32_e32 v60, v60, v100
	ds_read_b128 v[34:37], v101 offset:10240
	ds_read_b128 v[38:41], v101 offset:8192
	ds_read_b128 v[42:45], v101 offset:8208
	ds_read_b128 v[46:49], v101 offset:10256
	s_waitcnt lgkmcnt(4)
	v_mul_f32_e32 v61, v104, v30
	v_mul_f32_e32 v100, v105, v8
	v_fmac_f32_e32 v61, v108, v26
	v_add_f32_e32 v61, 0, v61
	v_fmac_f32_e32 v100, v109, v12
	v_add_f32_e32 v61, v61, v100
	v_mul_f32_e32 v100, v106, v31
	v_fmac_f32_e32 v100, v110, v27
	v_add_f32_e32 v61, v61, v100
	v_mul_f32_e32 v100, v107, v9
	v_fmac_f32_e32 v100, v111, v13
	v_add_f32_e32 v61, v61, v100
	v_mul_f32_e32 v100, v116, v32
	v_fmac_f32_e32 v100, v112, v28
	v_add_f32_e32 v61, v61, v100
	v_mul_f32_e32 v100, v117, v10
	v_fmac_f32_e32 v100, v113, v14
	v_add_f32_e32 v61, v61, v100
	v_mul_f32_e32 v100, v118, v33
	v_fmac_f32_e32 v100, v114, v29
	v_add_f32_e32 v61, v61, v100
	v_mul_f32_e32 v100, v119, v11
	v_fmac_f32_e32 v100, v115, v15
	v_add_f32_e32 v61, v61, v100
	ds_read_b128 v[104:107], v101 offset:14336
	ds_read_b128 v[108:111], v101 offset:12288
	ds_read_b128 v[112:115], v101 offset:12304
	ds_read_b128 v[116:119], v101 offset:14352
	s_waitcnt lgkmcnt(4)
	v_mul_f32_e32 v62, v34, v30
	v_mul_f32_e32 v100, v35, v8
	v_fmac_f32_e32 v62, v38, v26
	v_add_f32_e32 v62, 0, v62
	v_fmac_f32_e32 v100, v39, v12
	v_add_f32_e32 v62, v62, v100
	v_mul_f32_e32 v100, v36, v31
	v_fmac_f32_e32 v100, v40, v27
	v_add_f32_e32 v62, v62, v100
	v_mul_f32_e32 v100, v37, v9
	v_fmac_f32_e32 v100, v41, v13
	v_add_f32_e32 v62, v62, v100
	v_mul_f32_e32 v100, v46, v32
	v_fmac_f32_e32 v100, v42, v28
	v_add_f32_e32 v62, v62, v100
	v_mul_f32_e32 v100, v47, v10
	v_fmac_f32_e32 v100, v43, v14
	v_add_f32_e32 v62, v62, v100
	v_mul_f32_e32 v100, v48, v33
	v_fmac_f32_e32 v100, v44, v29
	v_add_f32_e32 v62, v62, v100
	v_mul_f32_e32 v100, v49, v11
	v_fmac_f32_e32 v100, v45, v15
	v_add_f32_e32 v62, v62, v100
	ds_read_b128 v[34:37], v101 offset:18432
	ds_read_b128 v[38:41], v101 offset:16384
	ds_read_b128 v[42:45], v101 offset:16400
	ds_read_b128 v[46:49], v101 offset:18448
	s_waitcnt lgkmcnt(4)
	v_mul_f32_e32 v63, v104, v30
	v_mul_f32_e32 v100, v105, v8
	v_fmac_f32_e32 v63, v108, v26
	v_add_f32_e32 v63, 0, v63
	v_fmac_f32_e32 v100, v109, v12
	v_add_f32_e32 v63, v63, v100
	v_mul_f32_e32 v100, v106, v31
	v_fmac_f32_e32 v100, v110, v27
	v_add_f32_e32 v63, v63, v100
	v_mul_f32_e32 v100, v107, v9
	v_fmac_f32_e32 v100, v111, v13
	v_add_f32_e32 v63, v63, v100
	v_mul_f32_e32 v100, v116, v32
	v_fmac_f32_e32 v100, v112, v28
	v_add_f32_e32 v63, v63, v100
	v_mul_f32_e32 v100, v117, v10
	v_fmac_f32_e32 v100, v113, v14
	v_add_f32_e32 v63, v63, v100
	v_mul_f32_e32 v100, v118, v33
	v_fmac_f32_e32 v100, v114, v29
	v_add_f32_e32 v63, v63, v100
	v_mul_f32_e32 v100, v119, v11
	v_fmac_f32_e32 v100, v115, v15
	v_add_f32_e32 v63, v63, v100
	ds_read_b128 v[104:107], v101 offset:22528
	ds_read_b128 v[108:111], v101 offset:20480
	ds_read_b128 v[112:115], v101 offset:20496
	ds_read_b128 v[116:119], v101 offset:22544
	s_waitcnt lgkmcnt(4)
	v_mul_f32_e32 v64, v34, v30
	v_mul_f32_e32 v100, v35, v8
	v_fmac_f32_e32 v64, v38, v26
	v_add_f32_e32 v64, 0, v64
	v_fmac_f32_e32 v100, v39, v12
	v_add_f32_e32 v64, v64, v100
	v_mul_f32_e32 v100, v36, v31
	v_fmac_f32_e32 v100, v40, v27
	v_add_f32_e32 v64, v64, v100
	v_mul_f32_e32 v100, v37, v9
	v_fmac_f32_e32 v100, v41, v13
	v_add_f32_e32 v64, v64, v100
	v_mul_f32_e32 v100, v46, v32
	v_fmac_f32_e32 v100, v42, v28
	v_add_f32_e32 v64, v64, v100
	v_mul_f32_e32 v100, v47, v10
	v_fmac_f32_e32 v100, v43, v14
	v_add_f32_e32 v64, v64, v100
	v_mul_f32_e32 v100, v48, v33
	v_fmac_f32_e32 v100, v44, v29
	v_add_f32_e32 v64, v64, v100
	v_mul_f32_e32 v100, v49, v11
	v_fmac_f32_e32 v100, v45, v15
	v_add_f32_e32 v64, v64, v100
	ds_read_b128 v[34:37], v101 offset:26624
	ds_read_b128 v[38:41], v101 offset:24576
	ds_read_b128 v[42:45], v101 offset:24592
	ds_read_b128 v[46:49], v101 offset:26640
	s_waitcnt lgkmcnt(4)
	v_mul_f32_e32 v65, v104, v30
	v_mul_f32_e32 v100, v105, v8
	v_fmac_f32_e32 v65, v108, v26
	v_add_f32_e32 v65, 0, v65
	v_fmac_f32_e32 v100, v109, v12
	v_add_f32_e32 v65, v65, v100
	v_mul_f32_e32 v100, v106, v31
	v_fmac_f32_e32 v100, v110, v27
	v_add_f32_e32 v65, v65, v100
	v_mul_f32_e32 v100, v107, v9
	v_fmac_f32_e32 v100, v111, v13
	v_add_f32_e32 v65, v65, v100
	v_mul_f32_e32 v100, v116, v32
	v_fmac_f32_e32 v100, v112, v28
	v_add_f32_e32 v65, v65, v100
	v_mul_f32_e32 v100, v117, v10
	v_fmac_f32_e32 v100, v113, v14
	v_add_f32_e32 v65, v65, v100
	v_mul_f32_e32 v100, v118, v33
	v_fmac_f32_e32 v100, v114, v29
	v_add_f32_e32 v65, v65, v100
	v_mul_f32_e32 v100, v119, v11
	v_fmac_f32_e32 v100, v115, v15
	v_add_f32_e32 v65, v65, v100
	ds_read_b128 v[104:107], v101 offset:30720
	ds_read_b128 v[108:111], v101 offset:28672
	ds_read_b128 v[112:115], v101 offset:28688
	ds_read_b128 v[116:119], v101 offset:30736
	s_waitcnt lgkmcnt(4)
	v_mul_f32_e32 v66, v34, v30
	v_mul_f32_e32 v100, v35, v8
	v_fmac_f32_e32 v66, v38, v26
	v_add_f32_e32 v66, 0, v66
	v_fmac_f32_e32 v100, v39, v12
	v_add_f32_e32 v66, v66, v100
	v_mul_f32_e32 v100, v36, v31
	v_fmac_f32_e32 v100, v40, v27
	v_add_f32_e32 v66, v66, v100
	v_mul_f32_e32 v100, v37, v9
	v_fmac_f32_e32 v100, v41, v13
	v_add_f32_e32 v66, v66, v100
	v_mul_f32_e32 v100, v46, v32
	v_fmac_f32_e32 v100, v42, v28
	v_add_f32_e32 v66, v66, v100
	v_mul_f32_e32 v100, v47, v10
	v_fmac_f32_e32 v100, v43, v14
	v_add_f32_e32 v66, v66, v100
	v_mul_f32_e32 v100, v48, v33
	v_fmac_f32_e32 v100, v44, v29
	v_add_f32_e32 v66, v66, v100
	v_mul_f32_e32 v100, v49, v11
	v_fmac_f32_e32 v100, v45, v15
	v_add_f32_e32 v66, v66, v100
	ds_read_b128 v[34:37], v102 offset:2048
	ds_read_b128 v[38:41], v102
	ds_read_b128 v[42:45], v102 offset:16
	ds_read_b128 v[46:49], v102 offset:2064
	s_waitcnt lgkmcnt(4)
	v_mul_f32_e32 v67, v104, v30
	v_mul_f32_e32 v100, v105, v8
	v_fmac_f32_e32 v67, v108, v26
	v_add_f32_e32 v67, 0, v67
	v_fmac_f32_e32 v100, v109, v12
	v_add_f32_e32 v67, v67, v100
	v_mul_f32_e32 v100, v106, v31
	v_fmac_f32_e32 v100, v110, v27
	v_add_f32_e32 v67, v67, v100
	v_mul_f32_e32 v100, v107, v9
	v_fmac_f32_e32 v100, v111, v13
	v_add_f32_e32 v67, v67, v100
	v_mul_f32_e32 v100, v116, v32
	v_fmac_f32_e32 v100, v112, v28
	v_add_f32_e32 v67, v67, v100
	v_mul_f32_e32 v100, v117, v10
	v_fmac_f32_e32 v100, v113, v14
	v_add_f32_e32 v67, v67, v100
	v_mul_f32_e32 v100, v118, v33
	v_fmac_f32_e32 v100, v114, v29
	v_add_f32_e32 v67, v67, v100
	v_mul_f32_e32 v100, v119, v11
	v_fmac_f32_e32 v100, v115, v15
	v_add_f32_e32 v67, v67, v100
	s_waitcnt lgkmcnt(0)
	v_mul_f32_e32 v68, v34, v30
	v_mul_f32_e32 v100, v35, v8
	v_fmac_f32_e32 v68, v38, v26
	v_add_f32_e32 v68, 0, v68
	v_fmac_f32_e32 v100, v39, v12
	v_add_f32_e32 v68, v68, v100
	v_mul_f32_e32 v100, v36, v31
	v_fmac_f32_e32 v100, v40, v27
	v_add_f32_e32 v68, v68, v100
	v_mul_f32_e32 v100, v37, v9
	v_fmac_f32_e32 v100, v41, v13
	v_add_f32_e32 v68, v68, v100
	v_mul_f32_e32 v100, v46, v32
	v_fmac_f32_e32 v100, v42, v28
	v_add_f32_e32 v68, v68, v100
	v_mul_f32_e32 v100, v47, v10
	v_fmac_f32_e32 v100, v43, v14
	v_add_f32_e32 v68, v68, v100
	v_mul_f32_e32 v100, v48, v33
	v_fmac_f32_e32 v100, v44, v29
	v_add_f32_e32 v68, v68, v100
	v_mul_f32_e32 v100, v49, v11
	v_fmac_f32_e32 v100, v45, v15
	v_add_f32_e32 v68, v68, v100
	ds_bpermute_b32 v69, v16, v52
	ds_bpermute_b32 v70, v16, v53
	ds_bpermute_b32 v71, v16, v54
	ds_bpermute_b32 v72, v16, v55
	ds_bpermute_b32 v73, v16, v56
	ds_bpermute_b32 v74, v16, v57
	ds_bpermute_b32 v75, v16, v58
	ds_bpermute_b32 v76, v16, v59
	ds_bpermute_b32 v77, v16, v60
	ds_bpermute_b32 v78, v16, v61
	ds_bpermute_b32 v79, v16, v62
	ds_bpermute_b32 v80, v16, v63
	ds_bpermute_b32 v81, v16, v64
	ds_bpermute_b32 v82, v16, v65
	ds_bpermute_b32 v83, v16, v66
	s_waitcnt lgkmcnt(7)
	v_add_f32_e32 v52, v52, v69
	v_add_f32_e32 v53, v53, v70
	v_add_f32_e32 v54, v54, v71
	v_add_f32_e32 v55, v55, v72
	v_add_f32_e32 v56, v56, v73
	v_add_f32_e32 v57, v57, v74
	v_add_f32_e32 v58, v58, v75
	v_add_f32_e32 v59, v59, v76
	ds_bpermute_b32 v84, v16, v67
	ds_bpermute_b32 v85, v16, v68
	s_waitcnt lgkmcnt(2)
	v_add_f32_e32 v60, v60, v77
	v_add_f32_e32 v61, v61, v78
	v_add_f32_e32 v62, v62, v79
	v_add_f32_e32 v63, v63, v80
	v_add_f32_e32 v64, v64, v81
	v_add_f32_e32 v65, v65, v82
	v_add_f32_e32 v66, v66, v83
	s_waitcnt lgkmcnt(0)
	v_add_f32_e32 v67, v67, v84
	v_add_f32_e32 v68, v68, v85
	ds_bpermute_b32 v69, v21, v52
	ds_bpermute_b32 v70, v21, v53
	ds_bpermute_b32 v71, v21, v54
	ds_bpermute_b32 v72, v21, v55
	ds_bpermute_b32 v73, v21, v56
	ds_bpermute_b32 v74, v21, v57
	ds_bpermute_b32 v75, v21, v58
	ds_bpermute_b32 v76, v21, v59
	ds_bpermute_b32 v77, v21, v60
	ds_bpermute_b32 v78, v21, v61
	ds_bpermute_b32 v79, v21, v62
	ds_bpermute_b32 v80, v21, v63
	ds_bpermute_b32 v81, v21, v64
	ds_bpermute_b32 v82, v21, v65
	ds_bpermute_b32 v83, v21, v66
	s_waitcnt lgkmcnt(7)
	v_add_f32_e32 v52, v52, v69
	v_add_f32_e32 v53, v53, v70
	v_add_f32_e32 v54, v54, v71
	v_add_f32_e32 v55, v55, v72
	v_add_f32_e32 v56, v56, v73
	v_add_f32_e32 v57, v57, v74
	v_add_f32_e32 v58, v58, v75
	v_add_f32_e32 v59, v59, v76
	ds_bpermute_b32 v84, v21, v67
	ds_bpermute_b32 v85, v21, v68
	s_waitcnt lgkmcnt(2)
	v_add_f32_e32 v60, v60, v77
	v_add_f32_e32 v61, v61, v78
	v_add_f32_e32 v62, v62, v79
	v_add_f32_e32 v63, v63, v80
	v_add_f32_e32 v64, v64, v81
	v_add_f32_e32 v65, v65, v82
	v_add_f32_e32 v66, v66, v83
	s_waitcnt lgkmcnt(0)
	v_add_f32_e32 v67, v67, v84
	v_add_f32_e32 v68, v68, v85
	ds_bpermute_b32 v69, v22, v52
	ds_bpermute_b32 v70, v22, v53
	ds_bpermute_b32 v71, v22, v54
	ds_bpermute_b32 v72, v22, v55
	ds_bpermute_b32 v73, v22, v56
	ds_bpermute_b32 v74, v22, v57
	ds_bpermute_b32 v75, v22, v58
	ds_bpermute_b32 v76, v22, v59
	ds_bpermute_b32 v77, v22, v60
	ds_bpermute_b32 v78, v22, v61
	ds_bpermute_b32 v79, v22, v62
	ds_bpermute_b32 v80, v22, v63
	ds_bpermute_b32 v81, v22, v64
	ds_bpermute_b32 v82, v22, v65
	ds_bpermute_b32 v83, v22, v66
	s_waitcnt lgkmcnt(7)
	v_add_f32_e32 v52, v52, v69
	v_add_f32_e32 v53, v53, v70
	v_add_f32_e32 v54, v54, v71
	v_add_f32_e32 v55, v55, v72
	v_add_f32_e32 v56, v56, v73
	v_add_f32_e32 v57, v57, v74
	v_add_f32_e32 v58, v58, v75
	v_add_f32_e32 v59, v59, v76
	ds_bpermute_b32 v84, v22, v67
	ds_bpermute_b32 v85, v22, v68
	s_waitcnt lgkmcnt(2)
	v_add_f32_e32 v60, v60, v77
	v_add_f32_e32 v61, v61, v78
	v_add_f32_e32 v62, v62, v79
	v_add_f32_e32 v63, v63, v80
	v_add_f32_e32 v64, v64, v81
	v_add_f32_e32 v65, v65, v82
	v_add_f32_e32 v66, v66, v83
	s_waitcnt lgkmcnt(0)
	v_add_f32_e32 v67, v67, v84
	v_add_f32_e32 v68, v68, v85
	ds_bpermute_b32 v69, v23, v52
	ds_bpermute_b32 v70, v23, v53
	ds_bpermute_b32 v71, v23, v54
	ds_bpermute_b32 v72, v23, v55
	ds_bpermute_b32 v73, v23, v56
	ds_bpermute_b32 v74, v23, v57
	ds_bpermute_b32 v75, v23, v58
	ds_bpermute_b32 v76, v23, v59
	ds_bpermute_b32 v77, v23, v60
	ds_bpermute_b32 v78, v23, v61
	ds_bpermute_b32 v79, v23, v62
	ds_bpermute_b32 v80, v23, v63
	ds_bpermute_b32 v81, v23, v64
	ds_bpermute_b32 v82, v23, v65
	ds_bpermute_b32 v83, v23, v66
	s_waitcnt lgkmcnt(7)
	v_add_f32_e32 v52, v52, v69
	v_add_f32_e32 v53, v53, v70
	v_add_f32_e32 v54, v54, v71
	v_add_f32_e32 v55, v55, v72
	v_add_f32_e32 v56, v56, v73
	v_add_f32_e32 v57, v57, v74
	v_add_f32_e32 v58, v58, v75
	v_add_f32_e32 v59, v59, v76
	ds_bpermute_b32 v84, v23, v67
	ds_bpermute_b32 v85, v23, v68
	s_waitcnt lgkmcnt(2)
	v_add_f32_e32 v60, v60, v77
	v_add_f32_e32 v61, v61, v78
	v_add_f32_e32 v62, v62, v79
	v_add_f32_e32 v63, v63, v80
	v_add_f32_e32 v64, v64, v81
	v_add_f32_e32 v65, v65, v82
	v_add_f32_e32 v66, v66, v83
	s_waitcnt lgkmcnt(0)
	v_add_f32_e32 v67, v67, v84
	v_add_f32_e32 v68, v68, v85
	ds_bpermute_b32 v69, v24, v52
	ds_bpermute_b32 v70, v24, v53
	ds_bpermute_b32 v71, v24, v54
	ds_bpermute_b32 v72, v24, v55
	ds_bpermute_b32 v73, v24, v56
	ds_bpermute_b32 v74, v24, v57
	ds_bpermute_b32 v75, v24, v58
	ds_bpermute_b32 v76, v24, v59
	ds_bpermute_b32 v77, v24, v60
	ds_bpermute_b32 v78, v24, v61
	ds_bpermute_b32 v79, v24, v62
	ds_bpermute_b32 v80, v24, v63
	ds_bpermute_b32 v81, v24, v64
	ds_bpermute_b32 v82, v24, v65
	ds_bpermute_b32 v83, v24, v66
	s_waitcnt lgkmcnt(7)
	v_add_f32_e32 v52, v52, v69
	v_add_f32_e32 v53, v53, v70
	v_add_f32_e32 v54, v54, v71
	v_add_f32_e32 v55, v55, v72
	v_add_f32_e32 v56, v56, v73
	v_add_f32_e32 v57, v57, v74
	v_add_f32_e32 v58, v58, v75
	v_add_f32_e32 v59, v59, v76
	ds_bpermute_b32 v84, v24, v67
	ds_bpermute_b32 v85, v24, v68
	s_waitcnt lgkmcnt(2)
	v_add_f32_e32 v60, v60, v77
	v_add_f32_e32 v61, v61, v78
	v_add_f32_e32 v62, v62, v79
	v_add_f32_e32 v63, v63, v80
	v_add_f32_e32 v64, v64, v81
	v_add_f32_e32 v65, v65, v82
	v_add_f32_e32 v66, v66, v83
	s_waitcnt lgkmcnt(0)
	v_add_f32_e32 v67, v67, v84
	v_add_f32_e32 v68, v68, v85
	ds_bpermute_b32 v69, v25, v52
	ds_bpermute_b32 v70, v25, v53
	ds_bpermute_b32 v71, v25, v54
	ds_bpermute_b32 v72, v25, v55
	ds_bpermute_b32 v73, v25, v56
	ds_bpermute_b32 v74, v25, v57
	ds_bpermute_b32 v75, v25, v58
	ds_bpermute_b32 v76, v25, v59
	ds_bpermute_b32 v77, v25, v60
	ds_bpermute_b32 v78, v25, v61
	ds_bpermute_b32 v79, v25, v62
	ds_bpermute_b32 v80, v25, v63
	ds_bpermute_b32 v81, v25, v64
	ds_bpermute_b32 v82, v25, v65
	ds_bpermute_b32 v83, v25, v66
	s_waitcnt lgkmcnt(7)
	v_add_f32_e32 v52, v52, v69
	v_add_f32_e32 v53, v53, v70
	v_add_f32_e32 v54, v54, v71
	v_add_f32_e32 v55, v55, v72
	v_add_f32_e32 v56, v56, v73
	v_add_f32_e32 v57, v57, v74
	v_add_f32_e32 v58, v58, v75
	v_add_f32_e32 v59, v59, v76
	ds_bpermute_b32 v84, v25, v67
	ds_bpermute_b32 v85, v25, v68
	s_waitcnt lgkmcnt(2)
	v_add_f32_e32 v60, v60, v77
	v_add_f32_e32 v61, v61, v78
	v_add_f32_e32 v62, v62, v79
	v_add_f32_e32 v63, v63, v80
	v_add_f32_e32 v64, v64, v81
	v_add_f32_e32 v65, v65, v82
	v_add_f32_e32 v66, v66, v83
	s_waitcnt lgkmcnt(0)
	v_add_f32_e32 v67, v67, v84
	v_add_f32_e32 v68, v68, v85
	s_and_saveexec_b64 s[12:13], s[0:1]
	s_cbranch_execz .Lsg_a_skip
	global_store_dword v17, v52, s[10:11]
	s_add_u32 s10, s10, 0x4000
	s_addc_u32 s11, s11, 0
	global_store_dword v17, v53, s[10:11]
	s_add_u32 s10, s10, 0x4000
	s_addc_u32 s11, s11, 0
	global_store_dword v17, v54, s[10:11]
	s_add_u32 s10, s10, 0x4000
	s_addc_u32 s11, s11, 0
	global_store_dword v17, v55, s[10:11]
	s_add_u32 s10, s10, 0x4000
	s_addc_u32 s11, s11, 0
	global_store_dword v17, v56, s[10:11]
	s_add_u32 s10, s10, 0x4000
	s_addc_u32 s11, s11, 0
	global_store_dword v17, v57, s[10:11]
	s_add_u32 s10, s10, 0x4000
	s_addc_u32 s11, s11, 0
	global_store_dword v17, v58, s[10:11]
	s_add_u32 s10, s10, 0x4000
	s_addc_u32 s11, s11, 0
	global_store_dword v17, v59, s[10:11]
	s_add_u32 s10, s10, 0x4000
	s_addc_u32 s11, s11, 0
	global_store_dword v17, v60, s[10:11]
	s_add_u32 s10, s10, 0x4000
	s_addc_u32 s11, s11, 0
	global_store_dword v17, v61, s[10:11]
	s_add_u32 s10, s10, 0x4000
	s_addc_u32 s11, s11, 0
	global_store_dword v17, v62, s[10:11]
	s_add_u32 s10, s10, 0x4000
	s_addc_u32 s11, s11, 0
	global_store_dword v17, v63, s[10:11]
	s_add_u32 s10, s10, 0x4000
	s_addc_u32 s11, s11, 0
	global_store_dword v17, v64, s[10:11]
	s_add_u32 s10, s10, 0x4000
	s_addc_u32 s11, s11, 0
	global_store_dword v17, v65, s[10:11]
	s_add_u32 s10, s10, 0x4000
	s_addc_u32 s11, s11, 0
	global_store_dword v17, v66, s[10:11]
	s_add_u32 s10, s10, 0x4000
	s_addc_u32 s11, s11, 0
	global_store_dword v17, v67, s[10:11]
	s_add_u32 s10, s10, 0x4000
	s_addc_u32 s11, s11, 0
	global_store_dword v17, v68, s[10:11]
.Lsg_a_skip:
	s_or_b64 exec, exec, s[12:13]
	s_branch .LBB0_110

.LBB0_131:
	v_lshlrev_b32_e32 v26, 16, v12
	v_and_b32_e32 v12, 0xffff0000, v12
	v_lshlrev_b32_e32 v27, 16, v13
	v_and_b32_e32 v13, 0xffff0000, v13
	v_lshlrev_b32_e32 v28, 16, v14
	v_and_b32_e32 v14, 0xffff0000, v14
	v_lshlrev_b32_e32 v29, 16, v15
	v_and_b32_e32 v15, 0xffff0000, v15
	v_lshlrev_b32_e32 v30, 16, v8
	v_and_b32_e32 v8, 0xffff0000, v8
	v_lshlrev_b32_e32 v31, 16, v9
	v_and_b32_e32 v9, 0xffff0000, v9
	v_lshlrev_b32_e32 v32, 16, v10
	v_and_b32_e32 v10, 0xffff0000, v10
	v_lshlrev_b32_e32 v33, 16, v11
	v_and_b32_e32 v11, 0xffff0000, v11
	v_add_u32_e32 v101, 0x8000, v20
	v_add_u32_e32 v102, 0x10000, v20
	s_mov_b64 s[10:11], s[6:7]
	s_waitcnt lgkmcnt(0)
	ds_read_b128 v[34:37], v20 offset:2048
	ds_read_b128 v[38:41], v20
	ds_read_b128 v[42:45], v20 offset:16
	ds_read_b128 v[46:49], v20 offset:2064
	ds_read_b128 v[104:107], v20 offset:6144
	ds_read_b128 v[108:111], v20 offset:4096
	ds_read_b128 v[112:115], v20 offset:4112
	ds_read_b128 v[116:119], v20 offset:6160
	s_waitcnt lgkmcnt(4)
	v_mul_f32_e32 v52, v34, v30
	v_mul_f32_e32 v100, v35, v8
	v_fmac_f32_e32 v52, v38, v26
	v_add_f32_e32 v52, 0, v52
	v_fmac_f32_e32 v100, v39, v12
	v_add_f32_e32 v52, v52, v100
	v_mul_f32_e32 v100, v36, v31
	v_fmac_f32_e32 v100, v40, v27
	v_add_f32_e32 v52, v52, v100
	v_mul_f32_e32 v100, v37, v9
	v_fmac_f32_e32 v100, v41, v13
	v_add_f32_e32 v52, v52, v100
	v_mul_f32_e32 v100, v46, v32
	v_fmac_f32_e32 v100, v42, v28
	v_add_f32_e32 v52, v52, v100
	v_mul_f32_e32 v100, v47, v10
	v_fmac_f32_e32 v100, v43, v14
	v_add_f32_e32 v52, v52, v100
	v_mul_f32_e32 v100, v48, v33
	v_fmac_f32_e32 v100, v44, v29
	v_add_f32_e32 v52, v52, v100
	v_mul_f32_e32 v100, v49, v11
	v_fmac_f32_e32 v100, v45, v15
	v_add_f32_e32 v52, v52, v100
	ds_read_b128 v[34:37], v20 offset:10240
	ds_read_b128 v[38:41], v20 offset:8192
	ds_read_b128 v[42:45], v20 offset:8208
	ds_read_b128 v[46:49], v20 offset:10256
	s_waitcnt lgkmcnt(4)
	v_mul_f32_e32 v53, v104, v30
	v_mul_f32_e32 v100, v105, v8
	v_fmac_f32_e32 v53, v108, v26
	v_add_f32_e32 v53, 0, v53
	v_fmac_f32_e32 v100, v109, v12
	v_add_f32_e32 v53, v53, v100
	v_mul_f32_e32 v100, v106, v31
	v_fmac_f32_e32 v100, v110, v27
	v_add_f32_e32 v53, v53, v100
	v_mul_f32_e32 v100, v107, v9
	v_fmac_f32_e32 v100, v111, v13
	v_add_f32_e32 v53, v53, v100
	v_mul_f32_e32 v100, v116, v32
	v_fmac_f32_e32 v100, v112, v28
	v_add_f32_e32 v53, v53, v100
	v_mul_f32_e32 v100, v117, v10
	v_fmac_f32_e32 v100, v113, v14
	v_add_f32_e32 v53, v53, v100
	v_mul_f32_e32 v100, v118, v33
	v_fmac_f32_e32 v100, v114, v29
	v_add_f32_e32 v53, v53, v100
	v_mul_f32_e32 v100, v119, v11
	v_fmac_f32_e32 v100, v115, v15
	v_add_f32_e32 v53, v53, v100
	ds_read_b128 v[104:107], v20 offset:14336
	ds_read_b128 v[108:111], v20 offset:12288
	ds_read_b128 v[112:115], v20 offset:12304
	ds_read_b128 v[116:119], v20 offset:14352
	s_waitcnt lgkmcnt(4)
	v_mul_f32_e32 v54, v34, v30
	v_mul_f32_e32 v100, v35, v8
	v_fmac_f32_e32 v54, v38, v26
	v_add_f32_e32 v54, 0, v54
	v_fmac_f32_e32 v100, v39, v12
	v_add_f32_e32 v54, v54, v100
	v_mul_f32_e32 v100, v36, v31
	v_fmac_f32_e32 v100, v40, v27
	v_add_f32_e32 v54, v54, v100
	v_mul_f32_e32 v100, v37, v9
	v_fmac_f32_e32 v100, v41, v13
	v_add_f32_e32 v54, v54, v100
	v_mul_f32_e32 v100, v46, v32
	v_fmac_f32_e32 v100, v42, v28
	v_add_f32_e32 v54, v54, v100
	v_mul_f32_e32 v100, v47, v10
	v_fmac_f32_e32 v100, v43, v14
	v_add_f32_e32 v54, v54, v100
	v_mul_f32_e32 v100, v48, v33
	v_fmac_f32_e32 v100, v44, v29
	v_add_f32_e32 v54, v54, v100
	v_mul_f32_e32 v100, v49, v11
	v_fmac_f32_e32 v100, v45, v15
	v_add_f32_e32 v54, v54, v100
	ds_read_b128 v[34:37], v20 offset:18432
	ds_read_b128 v[38:41], v20 offset:16384
	ds_read_b128 v[42:45], v20 offset:16400
	ds_read_b128 v[46:49], v20 offset:18448
	s_waitcnt lgkmcnt(4)
	v_mul_f32_e32 v55, v104, v30
	v_mul_f32_e32 v100, v105, v8
	v_fmac_f32_e32 v55, v108, v26
	v_add_f32_e32 v55, 0, v55
	v_fmac_f32_e32 v100, v109, v12
	v_add_f32_e32 v55, v55, v100
	v_mul_f32_e32 v100, v106, v31
	v_fmac_f32_e32 v100, v110, v27
	v_add_f32_e32 v55, v55, v100
	v_mul_f32_e32 v100, v107, v9
	v_fmac_f32_e32 v100, v111, v13
	v_add_f32_e32 v55, v55, v100
	v_mul_f32_e32 v100, v116, v32
	v_fmac_f32_e32 v100, v112, v28
	v_add_f32_e32 v55, v55, v100
	v_mul_f32_e32 v100, v117, v10
	v_fmac_f32_e32 v100, v113, v14
	v_add_f32_e32 v55, v55, v100
	v_mul_f32_e32 v100, v118, v33
	v_fmac_f32_e32 v100, v114, v29
	v_add_f32_e32 v55, v55, v100
	v_mul_f32_e32 v100, v119, v11
	v_fmac_f32_e32 v100, v115, v15
	v_add_f32_e32 v55, v55, v100
	ds_read_b128 v[104:107], v20 offset:22528
	ds_read_b128 v[108:111], v20 offset:20480
	ds_read_b128 v[112:115], v20 offset:20496
	ds_read_b128 v[116:119], v20 offset:22544
	s_waitcnt lgkmcnt(4)
	v_mul_f32_e32 v56, v34, v30
	v_mul_f32_e32 v100, v35, v8
	v_fmac_f32_e32 v56, v38, v26
	v_add_f32_e32 v56, 0, v56
	v_fmac_f32_e32 v100, v39, v12
	v_add_f32_e32 v56, v56, v100
	v_mul_f32_e32 v100, v36, v31
	v_fmac_f32_e32 v100, v40, v27
	v_add_f32_e32 v56, v56, v100
	v_mul_f32_e32 v100, v37, v9
	v_fmac_f32_e32 v100, v41, v13
	v_add_f32_e32 v56, v56, v100
	v_mul_f32_e32 v100, v46, v32
	v_fmac_f32_e32 v100, v42, v28
	v_add_f32_e32 v56, v56, v100
	v_mul_f32_e32 v100, v47, v10
	v_fmac_f32_e32 v100, v43, v14
	v_add_f32_e32 v56, v56, v100
	v_mul_f32_e32 v100, v48, v33
	v_fmac_f32_e32 v100, v44, v29
	v_add_f32_e32 v56, v56, v100
	v_mul_f32_e32 v100, v49, v11
	v_fmac_f32_e32 v100, v45, v15
	v_add_f32_e32 v56, v56, v100
	ds_read_b128 v[34:37], v20 offset:26624
	ds_read_b128 v[38:41], v20 offset:24576
	ds_read_b128 v[42:45], v20 offset:24592
	ds_read_b128 v[46:49], v20 offset:26640
	s_waitcnt lgkmcnt(4)
	v_mul_f32_e32 v57, v104, v30
	v_mul_f32_e32 v100, v105, v8
	v_fmac_f32_e32 v57, v108, v26
	v_add_f32_e32 v57, 0, v57
	v_fmac_f32_e32 v100, v109, v12
	v_add_f32_e32 v57, v57, v100
	v_mul_f32_e32 v100, v106, v31
	v_fmac_f32_e32 v100, v110, v27
	v_add_f32_e32 v57, v57, v100
	v_mul_f32_e32 v100, v107, v9
	v_fmac_f32_e32 v100, v111, v13
	v_add_f32_e32 v57, v57, v100
	v_mul_f32_e32 v100, v116, v32
	v_fmac_f32_e32 v100, v112, v28
	v_add_f32_e32 v57, v57, v100
	v_mul_f32_e32 v100, v117, v10
	v_fmac_f32_e32 v100, v113, v14
	v_add_f32_e32 v57, v57, v100
	v_mul_f32_e32 v100, v118, v33
	v_fmac_f32_e32 v100, v114, v29
	v_add_f32_e32 v57, v57, v100
	v_mul_f32_e32 v100, v119, v11
	v_fmac_f32_e32 v100, v115, v15
	v_add_f32_e32 v57, v57, v100
	ds_read_b128 v[104:107], v20 offset:30720
	ds_read_b128 v[108:111], v20 offset:28672
	ds_read_b128 v[112:115], v20 offset:28688
	ds_read_b128 v[116:119], v20 offset:30736
	s_waitcnt lgkmcnt(4)
	v_mul_f32_e32 v58, v34, v30
	v_mul_f32_e32 v100, v35, v8
	v_fmac_f32_e32 v58, v38, v26
	v_add_f32_e32 v58, 0, v58
	v_fmac_f32_e32 v100, v39, v12
	v_add_f32_e32 v58, v58, v100
	v_mul_f32_e32 v100, v36, v31
	v_fmac_f32_e32 v100, v40, v27
	v_add_f32_e32 v58, v58, v100
	v_mul_f32_e32 v100, v37, v9
	v_fmac_f32_e32 v100, v41, v13
	v_add_f32_e32 v58, v58, v100
	v_mul_f32_e32 v100, v46, v32
	v_fmac_f32_e32 v100, v42, v28
	v_add_f32_e32 v58, v58, v100
	v_mul_f32_e32 v100, v47, v10
	v_fmac_f32_e32 v100, v43, v14
	v_add_f32_e32 v58, v58, v100
	v_mul_f32_e32 v100, v48, v33
	v_fmac_f32_e32 v100, v44, v29
	v_add_f32_e32 v58, v58, v100
	v_mul_f32_e32 v100, v49, v11
	v_fmac_f32_e32 v100, v45, v15
	v_add_f32_e32 v58, v58, v100
	ds_read_b128 v[34:37], v101 offset:2048
	ds_read_b128 v[38:41], v101
	ds_read_b128 v[42:45], v101 offset:16
	ds_read_b128 v[46:49], v101 offset:2064
	s_waitcnt lgkmcnt(4)
	v_mul_f32_e32 v59, v104, v30
	v_mul_f32_e32 v100, v105, v8
	v_fmac_f32_e32 v59, v108, v26
	v_add_f32_e32 v59, 0, v59
	v_fmac_f32_e32 v100, v109, v12
	v_add_f32_e32 v59, v59, v100
	v_mul_f32_e32 v100, v106, v31
	v_fmac_f32_e32 v100, v110, v27
	v_add_f32_e32 v59, v59, v100
	v_mul_f32_e32 v100, v107, v9
	v_fmac_f32_e32 v100, v111, v13
	v_add_f32_e32 v59, v59, v100
	v_mul_f32_e32 v100, v116, v32
	v_fmac_f32_e32 v100, v112, v28
	v_add_f32_e32 v59, v59, v100
	v_mul_f32_e32 v100, v117, v10
	v_fmac_f32_e32 v100, v113, v14
	v_add_f32_e32 v59, v59, v100
	v_mul_f32_e32 v100, v118, v33
	v_fmac_f32_e32 v100, v114, v29
	v_add_f32_e32 v59, v59, v100
	v_mul_f32_e32 v100, v119, v11
	v_fmac_f32_e32 v100, v115, v15
	v_add_f32_e32 v59, v59, v100
	ds_read_b128 v[104:107], v101 offset:6144
	ds_read_b128 v[108:111], v101 offset:4096
	ds_read_b128 v[112:115], v101 offset:4112
	ds_read_b128 v[116:119], v101 offset:6160
	s_waitcnt lgkmcnt(4)
	v_mul_f32_e32 v60, v34, v30
	v_mul_f32_e32 v100, v35, v8
	v_fmac_f32_e32 v60, v38, v26
	v_add_f32_e32 v60, 0, v60
	v_fmac_f32_e32 v100, v39, v12
	v_add_f32_e32 v60, v60, v100
	v_mul_f32_e32 v100, v36, v31
	v_fmac_f32_e32 v100, v40, v27
	v_add_f32_e32 v60, v60, v100
	v_mul_f32_e32 v100, v37, v9
	v_fmac_f32_e32 v100, v41, v13
	v_add_f32_e32 v60, v60, v100
	v_mul_f32_e32 v100, v46, v32
	v_fmac_f32_e32 v100, v42, v28
	v_add_f32_e32 v60, v60, v100
	v_mul_f32_e32 v100, v47, v10
	v_fmac_f32_e32 v100, v43, v14
	v_add_f32_e32 v60, v60, v100
	v_mul_f32_e32 v100, v48, v33
	v_fmac_f32_e32 v100, v44, v29
	v_add_f32_e32 v60, v60, v100
	v_mul_f32_e32 v100, v49, v11
	v_fmac_f32_e32 v100, v45, v15
	v_add_f32_e32 v60, v60, v100
	ds_read_b128 v[34:37], v101 offset:10240
	ds_read_b128 v[38:41], v101 offset:8192
	ds_read_b128 v[42:45], v101 offset:8208
	ds_read_b128 v[46:49], v101 offset:10256
	s_waitcnt lgkmcnt(4)
	v_mul_f32_e32 v61, v104, v30
	v_mul_f32_e32 v100, v105, v8
	v_fmac_f32_e32 v61, v108, v26
	v_add_f32_e32 v61, 0, v61
	v_fmac_f32_e32 v100, v109, v12
	v_add_f32_e32 v61, v61, v100
	v_mul_f32_e32 v100, v106, v31
	v_fmac_f32_e32 v100, v110, v27
	v_add_f32_e32 v61, v61, v100
	v_mul_f32_e32 v100, v107, v9
	v_fmac_f32_e32 v100, v111, v13
	v_add_f32_e32 v61, v61, v100
	v_mul_f32_e32 v100, v116, v32
	v_fmac_f32_e32 v100, v112, v28
	v_add_f32_e32 v61, v61, v100
	v_mul_f32_e32 v100, v117, v10
	v_fmac_f32_e32 v100, v113, v14
	v_add_f32_e32 v61, v61, v100
	v_mul_f32_e32 v100, v118, v33
	v_fmac_f32_e32 v100, v114, v29
	v_add_f32_e32 v61, v61, v100
	v_mul_f32_e32 v100, v119, v11
	v_fmac_f32_e32 v100, v115, v15
	v_add_f32_e32 v61, v61, v100
	ds_read_b128 v[104:107], v101 offset:14336
	ds_read_b128 v[108:111], v101 offset:12288
	ds_read_b128 v[112:115], v101 offset:12304
	ds_read_b128 v[116:119], v101 offset:14352
	s_waitcnt lgkmcnt(4)
	v_mul_f32_e32 v62, v34, v30
	v_mul_f32_e32 v100, v35, v8
	v_fmac_f32_e32 v62, v38, v26
	v_add_f32_e32 v62, 0, v62
	v_fmac_f32_e32 v100, v39, v12
	v_add_f32_e32 v62, v62, v100
	v_mul_f32_e32 v100, v36, v31
	v_fmac_f32_e32 v100, v40, v27
	v_add_f32_e32 v62, v62, v100
	v_mul_f32_e32 v100, v37, v9
	v_fmac_f32_e32 v100, v41, v13
	v_add_f32_e32 v62, v62, v100
	v_mul_f32_e32 v100, v46, v32
	v_fmac_f32_e32 v100, v42, v28
	v_add_f32_e32 v62, v62, v100
	v_mul_f32_e32 v100, v47, v10
	v_fmac_f32_e32 v100, v43, v14
	v_add_f32_e32 v62, v62, v100
	v_mul_f32_e32 v100, v48, v33
	v_fmac_f32_e32 v100, v44, v29
	v_add_f32_e32 v62, v62, v100
	v_mul_f32_e32 v100, v49, v11
	v_fmac_f32_e32 v100, v45, v15
	v_add_f32_e32 v62, v62, v100
	ds_read_b128 v[34:37], v101 offset:18432
	ds_read_b128 v[38:41], v101 offset:16384
	ds_read_b128 v[42:45], v101 offset:16400
	ds_read_b128 v[46:49], v101 offset:18448
	s_waitcnt lgkmcnt(4)
	v_mul_f32_e32 v63, v104, v30
	v_mul_f32_e32 v100, v105, v8
	v_fmac_f32_e32 v63, v108, v26
	v_add_f32_e32 v63, 0, v63
	v_fmac_f32_e32 v100, v109, v12
	v_add_f32_e32 v63, v63, v100
	v_mul_f32_e32 v100, v106, v31
	v_fmac_f32_e32 v100, v110, v27
	v_add_f32_e32 v63, v63, v100
	v_mul_f32_e32 v100, v107, v9
	v_fmac_f32_e32 v100, v111, v13
	v_add_f32_e32 v63, v63, v100
	v_mul_f32_e32 v100, v116, v32
	v_fmac_f32_e32 v100, v112, v28
	v_add_f32_e32 v63, v63, v100
	v_mul_f32_e32 v100, v117, v10
	v_fmac_f32_e32 v100, v113, v14
	v_add_f32_e32 v63, v63, v100
	v_mul_f32_e32 v100, v118, v33
	v_fmac_f32_e32 v100, v114, v29
	v_add_f32_e32 v63, v63, v100
	v_mul_f32_e32 v100, v119, v11
	v_fmac_f32_e32 v100, v115, v15
	v_add_f32_e32 v63, v63, v100
	ds_read_b128 v[104:107], v101 offset:22528
	ds_read_b128 v[108:111], v101 offset:20480
	ds_read_b128 v[112:115], v101 offset:20496
	ds_read_b128 v[116:119], v101 offset:22544
	s_waitcnt lgkmcnt(4)
	v_mul_f32_e32 v64, v34, v30
	v_mul_f32_e32 v100, v35, v8
	v_fmac_f32_e32 v64, v38, v26
	v_add_f32_e32 v64, 0, v64
	v_fmac_f32_e32 v100, v39, v12
	v_add_f32_e32 v64, v64, v100
	v_mul_f32_e32 v100, v36, v31
	v_fmac_f32_e32 v100, v40, v27
	v_add_f32_e32 v64, v64, v100
	v_mul_f32_e32 v100, v37, v9
	v_fmac_f32_e32 v100, v41, v13
	v_add_f32_e32 v64, v64, v100
	v_mul_f32_e32 v100, v46, v32
	v_fmac_f32_e32 v100, v42, v28
	v_add_f32_e32 v64, v64, v100
	v_mul_f32_e32 v100, v47, v10
	v_fmac_f32_e32 v100, v43, v14
	v_add_f32_e32 v64, v64, v100
	v_mul_f32_e32 v100, v48, v33
	v_fmac_f32_e32 v100, v44, v29
	v_add_f32_e32 v64, v64, v100
	v_mul_f32_e32 v100, v49, v11
	v_fmac_f32_e32 v100, v45, v15
	v_add_f32_e32 v64, v64, v100
	ds_read_b128 v[34:37], v101 offset:26624
	ds_read_b128 v[38:41], v101 offset:24576
	ds_read_b128 v[42:45], v101 offset:24592
	ds_read_b128 v[46:49], v101 offset:26640
	s_waitcnt lgkmcnt(4)
	v_mul_f32_e32 v65, v104, v30
	v_mul_f32_e32 v100, v105, v8
	v_fmac_f32_e32 v65, v108, v26
	v_add_f32_e32 v65, 0, v65
	v_fmac_f32_e32 v100, v109, v12
	v_add_f32_e32 v65, v65, v100
	v_mul_f32_e32 v100, v106, v31
	v_fmac_f32_e32 v100, v110, v27
	v_add_f32_e32 v65, v65, v100
	v_mul_f32_e32 v100, v107, v9
	v_fmac_f32_e32 v100, v111, v13
	v_add_f32_e32 v65, v65, v100
	v_mul_f32_e32 v100, v116, v32
	v_fmac_f32_e32 v100, v112, v28
	v_add_f32_e32 v65, v65, v100
	v_mul_f32_e32 v100, v117, v10
	v_fmac_f32_e32 v100, v113, v14
	v_add_f32_e32 v65, v65, v100
	v_mul_f32_e32 v100, v118, v33
	v_fmac_f32_e32 v100, v114, v29
	v_add_f32_e32 v65, v65, v100
	v_mul_f32_e32 v100, v119, v11
	v_fmac_f32_e32 v100, v115, v15
	v_add_f32_e32 v65, v65, v100
	ds_read_b128 v[104:107], v101 offset:30720
	ds_read_b128 v[108:111], v101 offset:28672
	ds_read_b128 v[112:115], v101 offset:28688
	ds_read_b128 v[116:119], v101 offset:30736
	s_waitcnt lgkmcnt(4)
	v_mul_f32_e32 v66, v34, v30
	v_mul_f32_e32 v100, v35, v8
	v_fmac_f32_e32 v66, v38, v26
	v_add_f32_e32 v66, 0, v66
	v_fmac_f32_e32 v100, v39, v12
	v_add_f32_e32 v66, v66, v100
	v_mul_f32_e32 v100, v36, v31
	v_fmac_f32_e32 v100, v40, v27
	v_add_f32_e32 v66, v66, v100
	v_mul_f32_e32 v100, v37, v9
	v_fmac_f32_e32 v100, v41, v13
	v_add_f32_e32 v66, v66, v100
	v_mul_f32_e32 v100, v46, v32
	v_fmac_f32_e32 v100, v42, v28
	v_add_f32_e32 v66, v66, v100
	v_mul_f32_e32 v100, v47, v10
	v_fmac_f32_e32 v100, v43, v14
	v_add_f32_e32 v66, v66, v100
	v_mul_f32_e32 v100, v48, v33
	v_fmac_f32_e32 v100, v44, v29
	v_add_f32_e32 v66, v66, v100
	v_mul_f32_e32 v100, v49, v11
	v_fmac_f32_e32 v100, v45, v15
	v_add_f32_e32 v66, v66, v100
	ds_read_b128 v[34:37], v102 offset:2048
	ds_read_b128 v[38:41], v102
	ds_read_b128 v[42:45], v102 offset:16
	ds_read_b128 v[46:49], v102 offset:2064
	s_waitcnt lgkmcnt(4)
	v_mul_f32_e32 v67, v104, v30
	v_mul_f32_e32 v100, v105, v8
	v_fmac_f32_e32 v67, v108, v26
	v_add_f32_e32 v67, 0, v67
	v_fmac_f32_e32 v100, v109, v12
	v_add_f32_e32 v67, v67, v100
	v_mul_f32_e32 v100, v106, v31
	v_fmac_f32_e32 v100, v110, v27
	v_add_f32_e32 v67, v67, v100
	v_mul_f32_e32 v100, v107, v9
	v_fmac_f32_e32 v100, v111, v13
	v_add_f32_e32 v67, v67, v100
	v_mul_f32_e32 v100, v116, v32
	v_fmac_f32_e32 v100, v112, v28
	v_add_f32_e32 v67, v67, v100
	v_mul_f32_e32 v100, v117, v10
	v_fmac_f32_e32 v100, v113, v14
	v_add_f32_e32 v67, v67, v100
	v_mul_f32_e32 v100, v118, v33
	v_fmac_f32_e32 v100, v114, v29
	v_add_f32_e32 v67, v67, v100
	v_mul_f32_e32 v100, v119, v11
	v_fmac_f32_e32 v100, v115, v15
	v_add_f32_e32 v67, v67, v100
	s_waitcnt lgkmcnt(0)
	v_mul_f32_e32 v68, v34, v30
	v_mul_f32_e32 v100, v35, v8
	v_fmac_f32_e32 v68, v38, v26
	v_add_f32_e32 v68, 0, v68
	v_fmac_f32_e32 v100, v39, v12
	v_add_f32_e32 v68, v68, v100
	v_mul_f32_e32 v100, v36, v31
	v_fmac_f32_e32 v100, v40, v27
	v_add_f32_e32 v68, v68, v100
	v_mul_f32_e32 v100, v37, v9
	v_fmac_f32_e32 v100, v41, v13
	v_add_f32_e32 v68, v68, v100
	v_mul_f32_e32 v100, v46, v32
	v_fmac_f32_e32 v100, v42, v28
	v_add_f32_e32 v68, v68, v100
	v_mul_f32_e32 v100, v47, v10
	v_fmac_f32_e32 v100, v43, v14
	v_add_f32_e32 v68, v68, v100
	v_mul_f32_e32 v100, v48, v33
	v_fmac_f32_e32 v100, v44, v29
	v_add_f32_e32 v68, v68, v100
	v_mul_f32_e32 v100, v49, v11
	v_fmac_f32_e32 v100, v45, v15
	v_add_f32_e32 v68, v68, v100
	ds_bpermute_b32 v69, v16, v52
	ds_bpermute_b32 v70, v16, v53
	ds_bpermute_b32 v71, v16, v54
	ds_bpermute_b32 v72, v16, v55
	ds_bpermute_b32 v73, v16, v56
	ds_bpermute_b32 v74, v16, v57
	ds_bpermute_b32 v75, v16, v58
	ds_bpermute_b32 v76, v16, v59
	ds_bpermute_b32 v77, v16, v60
	ds_bpermute_b32 v78, v16, v61
	ds_bpermute_b32 v79, v16, v62
	ds_bpermute_b32 v80, v16, v63
	ds_bpermute_b32 v81, v16, v64
	ds_bpermute_b32 v82, v16, v65
	ds_bpermute_b32 v83, v16, v66
	s_waitcnt lgkmcnt(7)
	v_add_f32_e32 v52, v52, v69
	v_add_f32_e32 v53, v53, v70
	v_add_f32_e32 v54, v54, v71
	v_add_f32_e32 v55, v55, v72
	v_add_f32_e32 v56, v56, v73
	v_add_f32_e32 v57, v57, v74
	v_add_f32_e32 v58, v58, v75
	v_add_f32_e32 v59, v59, v76
	ds_bpermute_b32 v84, v16, v67
	ds_bpermute_b32 v85, v16, v68
	s_waitcnt lgkmcnt(2)
	v_add_f32_e32 v60, v60, v77
	v_add_f32_e32 v61, v61, v78
	v_add_f32_e32 v62, v62, v79
	v_add_f32_e32 v63, v63, v80
	v_add_f32_e32 v64, v64, v81
	v_add_f32_e32 v65, v65, v82
	v_add_f32_e32 v66, v66, v83
	s_waitcnt lgkmcnt(0)
	v_add_f32_e32 v67, v67, v84
	v_add_f32_e32 v68, v68, v85
	ds_bpermute_b32 v69, v21, v52
	ds_bpermute_b32 v70, v21, v53
	ds_bpermute_b32 v71, v21, v54
	ds_bpermute_b32 v72, v21, v55
	ds_bpermute_b32 v73, v21, v56
	ds_bpermute_b32 v74, v21, v57
	ds_bpermute_b32 v75, v21, v58
	ds_bpermute_b32 v76, v21, v59
	ds_bpermute_b32 v77, v21, v60
	ds_bpermute_b32 v78, v21, v61
	ds_bpermute_b32 v79, v21, v62
	ds_bpermute_b32 v80, v21, v63
	ds_bpermute_b32 v81, v21, v64
	ds_bpermute_b32 v82, v21, v65
	ds_bpermute_b32 v83, v21, v66
	s_waitcnt lgkmcnt(7)
	v_add_f32_e32 v52, v52, v69
	v_add_f32_e32 v53, v53, v70
	v_add_f32_e32 v54, v54, v71
	v_add_f32_e32 v55, v55, v72
	v_add_f32_e32 v56, v56, v73
	v_add_f32_e32 v57, v57, v74
	v_add_f32_e32 v58, v58, v75
	v_add_f32_e32 v59, v59, v76
	ds_bpermute_b32 v84, v21, v67
	ds_bpermute_b32 v85, v21, v68
	s_waitcnt lgkmcnt(2)
	v_add_f32_e32 v60, v60, v77
	v_add_f32_e32 v61, v61, v78
	v_add_f32_e32 v62, v62, v79
	v_add_f32_e32 v63, v63, v80
	v_add_f32_e32 v64, v64, v81
	v_add_f32_e32 v65, v65, v82
	v_add_f32_e32 v66, v66, v83
	s_waitcnt lgkmcnt(0)
	v_add_f32_e32 v67, v67, v84
	v_add_f32_e32 v68, v68, v85
	ds_bpermute_b32 v69, v22, v52
	ds_bpermute_b32 v70, v22, v53
	ds_bpermute_b32 v71, v22, v54
	ds_bpermute_b32 v72, v22, v55
	ds_bpermute_b32 v73, v22, v56
	ds_bpermute_b32 v74, v22, v57
	ds_bpermute_b32 v75, v22, v58
	ds_bpermute_b32 v76, v22, v59
	ds_bpermute_b32 v77, v22, v60
	ds_bpermute_b32 v78, v22, v61
	ds_bpermute_b32 v79, v22, v62
	ds_bpermute_b32 v80, v22, v63
	ds_bpermute_b32 v81, v22, v64
	ds_bpermute_b32 v82, v22, v65
	ds_bpermute_b32 v83, v22, v66
	s_waitcnt lgkmcnt(7)
	v_add_f32_e32 v52, v52, v69
	v_add_f32_e32 v53, v53, v70
	v_add_f32_e32 v54, v54, v71
	v_add_f32_e32 v55, v55, v72
	v_add_f32_e32 v56, v56, v73
	v_add_f32_e32 v57, v57, v74
	v_add_f32_e32 v58, v58, v75
	v_add_f32_e32 v59, v59, v76
	ds_bpermute_b32 v84, v22, v67
	ds_bpermute_b32 v85, v22, v68
	s_waitcnt lgkmcnt(2)
	v_add_f32_e32 v60, v60, v77
	v_add_f32_e32 v61, v61, v78
	v_add_f32_e32 v62, v62, v79
	v_add_f32_e32 v63, v63, v80
	v_add_f32_e32 v64, v64, v81
	v_add_f32_e32 v65, v65, v82
	v_add_f32_e32 v66, v66, v83
	s_waitcnt lgkmcnt(0)
	v_add_f32_e32 v67, v67, v84
	v_add_f32_e32 v68, v68, v85
	ds_bpermute_b32 v69, v23, v52
	ds_bpermute_b32 v70, v23, v53
	ds_bpermute_b32 v71, v23, v54
	ds_bpermute_b32 v72, v23, v55
	ds_bpermute_b32 v73, v23, v56
	ds_bpermute_b32 v74, v23, v57
	ds_bpermute_b32 v75, v23, v58
	ds_bpermute_b32 v76, v23, v59
	ds_bpermute_b32 v77, v23, v60
	ds_bpermute_b32 v78, v23, v61
	ds_bpermute_b32 v79, v23, v62
	ds_bpermute_b32 v80, v23, v63
	ds_bpermute_b32 v81, v23, v64
	ds_bpermute_b32 v82, v23, v65
	ds_bpermute_b32 v83, v23, v66
	s_waitcnt lgkmcnt(7)
	v_add_f32_e32 v52, v52, v69
	v_add_f32_e32 v53, v53, v70
	v_add_f32_e32 v54, v54, v71
	v_add_f32_e32 v55, v55, v72
	v_add_f32_e32 v56, v56, v73
	v_add_f32_e32 v57, v57, v74
	v_add_f32_e32 v58, v58, v75
	v_add_f32_e32 v59, v59, v76
	ds_bpermute_b32 v84, v23, v67
	ds_bpermute_b32 v85, v23, v68
	s_waitcnt lgkmcnt(2)
	v_add_f32_e32 v60, v60, v77
	v_add_f32_e32 v61, v61, v78
	v_add_f32_e32 v62, v62, v79
	v_add_f32_e32 v63, v63, v80
	v_add_f32_e32 v64, v64, v81
	v_add_f32_e32 v65, v65, v82
	v_add_f32_e32 v66, v66, v83
	s_waitcnt lgkmcnt(0)
	v_add_f32_e32 v67, v67, v84
	v_add_f32_e32 v68, v68, v85
	ds_bpermute_b32 v69, v24, v52
	ds_bpermute_b32 v70, v24, v53
	ds_bpermute_b32 v71, v24, v54
	ds_bpermute_b32 v72, v24, v55
	ds_bpermute_b32 v73, v24, v56
	ds_bpermute_b32 v74, v24, v57
	ds_bpermute_b32 v75, v24, v58
	ds_bpermute_b32 v76, v24, v59
	ds_bpermute_b32 v77, v24, v60
	ds_bpermute_b32 v78, v24, v61
	ds_bpermute_b32 v79, v24, v62
	ds_bpermute_b32 v80, v24, v63
	ds_bpermute_b32 v81, v24, v64
	ds_bpermute_b32 v82, v24, v65
	ds_bpermute_b32 v83, v24, v66
	s_waitcnt lgkmcnt(7)
	v_add_f32_e32 v52, v52, v69
	v_add_f32_e32 v53, v53, v70
	v_add_f32_e32 v54, v54, v71
	v_add_f32_e32 v55, v55, v72
	v_add_f32_e32 v56, v56, v73
	v_add_f32_e32 v57, v57, v74
	v_add_f32_e32 v58, v58, v75
	v_add_f32_e32 v59, v59, v76
	ds_bpermute_b32 v84, v24, v67
	ds_bpermute_b32 v85, v24, v68
	s_waitcnt lgkmcnt(2)
	v_add_f32_e32 v60, v60, v77
	v_add_f32_e32 v61, v61, v78
	v_add_f32_e32 v62, v62, v79
	v_add_f32_e32 v63, v63, v80
	v_add_f32_e32 v64, v64, v81
	v_add_f32_e32 v65, v65, v82
	v_add_f32_e32 v66, v66, v83
	s_waitcnt lgkmcnt(0)
	v_add_f32_e32 v67, v67, v84
	v_add_f32_e32 v68, v68, v85
	ds_bpermute_b32 v69, v25, v52
	ds_bpermute_b32 v70, v25, v53
	ds_bpermute_b32 v71, v25, v54
	ds_bpermute_b32 v72, v25, v55
	ds_bpermute_b32 v73, v25, v56
	ds_bpermute_b32 v74, v25, v57
	ds_bpermute_b32 v75, v25, v58
	ds_bpermute_b32 v76, v25, v59
	ds_bpermute_b32 v77, v25, v60
	ds_bpermute_b32 v78, v25, v61
	ds_bpermute_b32 v79, v25, v62
	ds_bpermute_b32 v80, v25, v63
	ds_bpermute_b32 v81, v25, v64
	ds_bpermute_b32 v82, v25, v65
	ds_bpermute_b32 v83, v25, v66
	s_waitcnt lgkmcnt(7)
	v_add_f32_e32 v52, v52, v69
	v_add_f32_e32 v53, v53, v70
	v_add_f32_e32 v54, v54, v71
	v_add_f32_e32 v55, v55, v72
	v_add_f32_e32 v56, v56, v73
	v_add_f32_e32 v57, v57, v74
	v_add_f32_e32 v58, v58, v75
	v_add_f32_e32 v59, v59, v76
	ds_bpermute_b32 v84, v25, v67
	ds_bpermute_b32 v85, v25, v68
	s_waitcnt lgkmcnt(2)
	v_add_f32_e32 v60, v60, v77
	v_add_f32_e32 v61, v61, v78
	v_add_f32_e32 v62, v62, v79
	v_add_f32_e32 v63, v63, v80
	v_add_f32_e32 v64, v64, v81
	v_add_f32_e32 v65, v65, v82
	v_add_f32_e32 v66, v66, v83
	s_waitcnt lgkmcnt(0)
	v_add_f32_e32 v67, v67, v84
	v_add_f32_e32 v68, v68, v85
	s_and_saveexec_b64 s[12:13], s[0:1]
	s_cbranch_execz .Lsg_c_skip
	global_store_dword v17, v52, s[10:11]
	s_add_u32 s10, s10, 0x3000
	s_addc_u32 s11, s11, 0
	global_store_dword v17, v53, s[10:11]
	s_add_u32 s10, s10, 0x3000
	s_addc_u32 s11, s11, 0
	global_store_dword v17, v54, s[10:11]
	s_add_u32 s10, s10, 0x3000
	s_addc_u32 s11, s11, 0
	global_store_dword v17, v55, s[10:11]
	s_add_u32 s10, s10, 0x3000
	s_addc_u32 s11, s11, 0
	global_store_dword v17, v56, s[10:11]
	s_add_u32 s10, s10, 0x3000
	s_addc_u32 s11, s11, 0
	global_store_dword v17, v57, s[10:11]
	s_add_u32 s10, s10, 0x3000
	s_addc_u32 s11, s11, 0
	global_store_dword v17, v58, s[10:11]
	s_add_u32 s10, s10, 0x3000
	s_addc_u32 s11, s11, 0
	global_store_dword v17, v59, s[10:11]
	s_add_u32 s10, s10, 0x3000
	s_addc_u32 s11, s11, 0
	global_store_dword v17, v60, s[10:11]
	s_add_u32 s10, s10, 0x3000
	s_addc_u32 s11, s11, 0
	global_store_dword v17, v61, s[10:11]
	s_add_u32 s10, s10, 0x3000
	s_addc_u32 s11, s11, 0
	global_store_dword v17, v62, s[10:11]
	s_add_u32 s10, s10, 0x3000
	s_addc_u32 s11, s11, 0
	global_store_dword v17, v63, s[10:11]
	s_add_u32 s10, s10, 0x3000
	s_addc_u32 s11, s11, 0
	global_store_dword v17, v64, s[10:11]
	s_add_u32 s10, s10, 0x3000
	s_addc_u32 s11, s11, 0
	global_store_dword v17, v65, s[10:11]
	s_add_u32 s10, s10, 0x3000
	s_addc_u32 s11, s11, 0
	global_store_dword v17, v66, s[10:11]
	s_add_u32 s10, s10, 0x3000
	s_addc_u32 s11, s11, 0
	global_store_dword v17, v67, s[10:11]
	s_add_u32 s10, s10, 0x3000
	s_addc_u32 s11, s11, 0
	global_store_dword v17, v68, s[10:11]
